# seam 2 (phase 12): same software prefetch + counted vmcnt(16) as the final seam
# baseline (speedup 1.0000x reference)
.LBB0_1019:
	s_or_b64 exec, exec, s[0:1]
	s_waitcnt lgkmcnt(0)
	s_barrier
	s_and_saveexec_b64 s[8:9], s[86:87]
	s_cbranch_execz .LBB0_1024
	s_add_u32 s0, s66, 0x2000
	s_addc_u32 s1, s67, 0
	s_add_u32 s4, s36, 0x1000
	s_addc_u32 s5, s37, 0
	global_load_dwordx4 v[0:3], v150, s[0:1]
	global_load_dwordx4 v[4:7], v150, s[4:5]
	global_load_dwordx4 v[8:11], v152, s[0:1]
	global_load_dwordx4 v[12:15], v152, s[4:5]
	global_load_dwordx4 v[16:19], v154, s[0:1]
	global_load_dwordx4 v[20:23], v154, s[4:5]
	global_load_dwordx4 v[24:27], v144, s[0:1]
	global_load_dwordx4 v[28:31], v144, s[4:5]
	v_mbcnt_hi_u32_b32 v32, -1, v167
	v_and_b32_e32 v33, 64, v32
	v_add_u32_e32 v33, 64, v33
	v_xor_b32_e32 v34, 32, v32
	v_cmp_lt_i32_e32 vcc, v34, v33
	v_mov_b32_e32 v145, 0
	v_mov_b32_e32 v35, v145
	v_cndmask_b32_e32 v34, v32, v34, vcc
	v_lshlrev_b32_e32 v124, 2, v34
	v_xor_b32_e32 v34, 16, v32
	v_cmp_lt_i32_e32 vcc, v34, v33
	s_mov_b64 s[10:11], 0x1000
	v_mov_b32_e32 v130, -1
	v_cndmask_b32_e32 v34, v32, v34, vcc
	v_lshlrev_b32_e32 v125, 2, v34
	v_xor_b32_e32 v34, 8, v32
	v_cmp_lt_i32_e32 vcc, v34, v33
	v_lshlrev_b32_e32 v80, 3, v147
	v_mov_b32_e32 v81, v145
	v_cndmask_b32_e32 v34, v32, v34, vcc
	v_lshlrev_b32_e32 v126, 2, v34
	v_xor_b32_e32 v34, 4, v32
	v_cmp_lt_i32_e32 vcc, v34, v33
	s_mov_b64 s[12:13], 0
	s_mov_b64 s[14:15], 0x3222000
	v_cndmask_b32_e32 v34, v32, v34, vcc
	v_lshlrev_b32_e32 v127, 2, v34
	v_xor_b32_e32 v34, 2, v32
	v_cmp_lt_i32_e32 vcc, v34, v33
	s_mov_b32 s3, 0x3222000
	s_mov_b64 s[16:17], 0x3222200
	v_cndmask_b32_e32 v34, v32, v34, vcc
	v_lshlrev_b32_e32 v128, 2, v34
	v_xor_b32_e32 v34, 1, v32
	v_cmp_lt_i32_e32 vcc, v34, v33
	s_mov_b64 s[18:19], 0x3222400
	s_mov_b64 s[20:21], 0x3222600
	v_cndmask_b32_e32 v32, v32, v34, vcc
	v_lshlrev_b32_e32 v129, 2, v32
	v_lshlrev_b64 v[32:33], 11, v[148:149]
	v_mov_b32_e32 v34, v145
	v_lshl_add_u64 v[82:83], s[34:35], 0, v[32:33]
	v_lshl_add_u64 v[84:85], s[30:31], 0, v[32:33]
	v_mov_b32_e32 v32, v145
	v_mov_b32_e32 v33, v145
	v_mov_b64_e32 v[46:47], v[34:35]
	v_mov_b64_e32 v[62:63], v[34:35]
	v_mov_b64_e32 v[74:75], v[34:35]
	v_mov_b64_e32 v[38:39], v[34:35]
	v_mov_b64_e32 v[50:51], v[34:35]
	v_mov_b64_e32 v[58:59], v[34:35]
	v_mov_b64_e32 v[78:79], v[34:35]
	s_mov_b64 s[22:23], 0x3222800
	s_mov_b64 s[24:25], 0x3222a00
	s_mov_b64 s[38:39], 0x3222c00
	s_mov_b64 s[40:41], 0x3222e00
	s_movk_i32 s4, 0x1fff
	s_mov_b64 s[42:43], 0x5000
	s_mov_b64 s[44:45], 0x6000
	s_mov_b64 s[46:47], 0x7000
	s_mov_b32 s48, 0x3a800000
	s_mov_b32 s50, 0x358637bd
	s_mov_b32 s5, 0x800000
	s_mov_b32 s6, 0x15e22000
	v_mov_b64_e32 v[44:45], v[32:33]
	v_mov_b64_e32 v[60:61], v[32:33]
	v_mov_b64_e32 v[72:73], v[32:33]
	v_mov_b64_e32 v[36:37], v[32:33]
	v_mov_b64_e32 v[48:49], v[32:33]
	v_mov_b64_e32 v[56:57], v[32:33]
	v_mov_b64_e32 v[76:77], v[32:33]
	v_mov_b32_e32 v131, v148
	v_mov_b32_e32 v40, v145
	v_mov_b32_e32 v41, v145
	v_mov_b32_e32 v42, v145
	v_mov_b32_e32 v43, v145
	v_mov_b32_e32 v52, v145
	v_mov_b32_e32 v53, v145
	v_mov_b32_e32 v54, v145
	v_mov_b32_e32 v55, v145
	v_mov_b32_e32 v64, v145
	v_mov_b32_e32 v65, v145
	v_mov_b32_e32 v66, v145
	v_mov_b32_e32 v67, v145
	v_mov_b32_e32 v68, v145
	v_mov_b32_e32 v69, v145
	v_mov_b32_e32 v70, v145
	v_mov_b32_e32 v71, v145
	v_lshl_add_u64 v[238:239], v[84:85], 0, v[80:81]
	v_lshl_add_u64 v[240:241], v[82:83], 0, v[80:81]
	v_add_co_u32_e32 v240, vcc, s3, v240
	global_load_dwordx2 v[206:207], v[238:239], off
	global_load_dwordx2 v[208:209], v[238:239], off offset:512
	global_load_dwordx2 v[210:211], v[238:239], off offset:1024
	global_load_dwordx2 v[212:213], v[238:239], off offset:1536
	v_addc_co_u32_e32 v241, vcc, 0, v241, vcc
	global_load_dwordx2 v[214:215], v[240:241], off
	global_load_dwordx2 v[216:217], v[240:241], off offset:512
	global_load_dwordx2 v[218:219], v[240:241], off offset:1024
	global_load_dwordx2 v[220:221], v[240:241], off offset:1536
	global_load_dwordx2 v[222:223], v[238:239], off offset:2048
	global_load_dwordx2 v[224:225], v[238:239], off offset:2560
	global_load_dwordx2 v[226:227], v[238:239], off offset:3072
	global_load_dwordx2 v[228:229], v[238:239], off offset:3584
	global_load_dwordx2 v[230:231], v[240:241], off offset:2048
	global_load_dwordx2 v[232:233], v[240:241], off offset:2560
	global_load_dwordx2 v[234:235], v[240:241], off offset:3072
	global_load_dwordx2 v[236:237], v[240:241], off offset:3584
	s_branch .LBB0_1022
.LBB0_1021:
	s_or_b64 exec, exec, s[0:1]
	s_waitcnt vmcnt(16)
	v_mov_b64_e32 v[114:115], v[206:207]
	v_mov_b64_e32 v[100:101], v[208:209]
	v_mov_b64_e32 v[98:99], v[210:211]
	v_mov_b64_e32 v[94:95], v[212:213]
	v_mov_b64_e32 v[118:119], v[214:215]
	v_mov_b64_e32 v[116:117], v[216:217]
	v_mov_b64_e32 v[112:113], v[218:219]
	v_mov_b64_e32 v[110:111], v[220:221]
	v_mov_b64_e32 v[96:97], v[222:223]
	v_mov_b64_e32 v[92:93], v[224:225]
	v_mov_b64_e32 v[90:91], v[226:227]
	v_mov_b64_e32 v[88:89], v[228:229]
	v_mov_b64_e32 v[108:109], v[230:231]
	v_mov_b64_e32 v[106:107], v[232:233]
	v_mov_b64_e32 v[104:105], v[234:235]
	v_mov_b64_e32 v[102:103], v[236:237]
	v_add_u32_e32 v242, 2, v131
	v_cmp_lt_i32_e32 vcc, v242, v186
	s_and_saveexec_b64 s[26:27], vcc
	s_cbranch_execz .Ls2_nopf
	v_lshl_add_u64 v[238:239], v[84:85], 0, v[80:81]
	v_lshl_add_u64 v[240:241], v[86:87], 0, s[10:11]
	v_lshl_add_u64 v[238:239], v[238:239], 0, s[10:11]
	v_add_co_u32_e32 v240, vcc, s3, v240
	global_load_dwordx2 v[206:207], v[238:239], off
	global_load_dwordx2 v[208:209], v[238:239], off offset:512
	global_load_dwordx2 v[210:211], v[238:239], off offset:1024
	global_load_dwordx2 v[212:213], v[238:239], off offset:1536
	v_addc_co_u32_e32 v241, vcc, 0, v241, vcc
	global_load_dwordx2 v[214:215], v[240:241], off
	global_load_dwordx2 v[216:217], v[240:241], off offset:512
	global_load_dwordx2 v[218:219], v[240:241], off offset:1024
	global_load_dwordx2 v[220:221], v[240:241], off offset:1536
	global_load_dwordx2 v[222:223], v[238:239], off offset:2048
	global_load_dwordx2 v[224:225], v[238:239], off offset:2560
	global_load_dwordx2 v[226:227], v[238:239], off offset:3072
	global_load_dwordx2 v[228:229], v[238:239], off offset:3584
	global_load_dwordx2 v[230:231], v[240:241], off offset:2048
	global_load_dwordx2 v[232:233], v[240:241], off offset:2560
	global_load_dwordx2 v[234:235], v[240:241], off offset:3072
	global_load_dwordx2 v[236:237], v[240:241], off offset:3584
.Ls2_nopf:
	s_or_b64 exec, exec, s[26:27]
	v_and_b32_e32 v133, 0xffff0000, v118
	v_and_b32_e32 v141, 0xffff0000, v108
	v_lshlrev_b32_e32 v132, 16, v118
	v_lshlrev_b32_e32 v140, 16, v108
	v_mov_b32_e32 v178, v141
	v_mov_b32_e32 v179, v133
	v_lshlrev_b32_e32 v134, 16, v119
	v_lshlrev_b32_e32 v108, 16, v109
	v_mov_b32_e32 v176, v140
	v_mov_b32_e32 v177, v132
	v_pk_mul_f32 v[178:179], v[178:179], v[178:179]
	v_and_b32_e32 v135, 0xffff0000, v119
	v_and_b32_e32 v109, 0xffff0000, v109
	v_pk_fma_f32 v[176:177], v[176:177], v[176:177], v[178:179]
	v_mov_b32_e32 v178, v108
	v_mov_b32_e32 v179, v134
	v_lshlrev_b32_e32 v136, 16, v116
	v_lshlrev_b32_e32 v142, 16, v106
	v_pk_fma_f32 v[176:177], v[178:179], v[178:179], v[176:177]
	v_mov_b32_e32 v178, v109
	v_mov_b32_e32 v179, v135
	v_and_b32_e32 v137, 0xffff0000, v116
	v_and_b32_e32 v143, 0xffff0000, v106
	v_pk_fma_f32 v[176:177], v[178:179], v[178:179], v[176:177]
	v_mov_b32_e32 v178, v142
	v_mov_b32_e32 v179, v136
	v_lshlrev_b32_e32 v138, 16, v117
	v_lshlrev_b32_e32 v106, 16, v107
	v_pk_fma_f32 v[176:177], v[178:179], v[178:179], v[176:177]
	v_mov_b32_e32 v178, v143
	v_mov_b32_e32 v179, v137
	v_and_b32_e32 v139, 0xffff0000, v117
	v_and_b32_e32 v107, 0xffff0000, v107
	v_pk_fma_f32 v[176:177], v[178:179], v[178:179], v[176:177]
	v_mov_b32_e32 v178, v106
	v_mov_b32_e32 v179, v138
	v_lshlrev_b32_e32 v118, 16, v112
	v_lshlrev_b32_e32 v168, 16, v104
	v_pk_fma_f32 v[176:177], v[178:179], v[178:179], v[176:177]
	v_mov_b32_e32 v178, v107
	v_mov_b32_e32 v179, v139
	v_and_b32_e32 v119, 0xffff0000, v112
	v_and_b32_e32 v169, 0xffff0000, v104
	v_pk_fma_f32 v[176:177], v[178:179], v[178:179], v[176:177]
	v_mov_b32_e32 v178, v168
	v_mov_b32_e32 v179, v118
	v_lshlrev_b32_e32 v116, 16, v113
	v_lshlrev_b32_e32 v104, 16, v105
	v_pk_fma_f32 v[176:177], v[178:179], v[178:179], v[176:177]
	v_mov_b32_e32 v178, v169
	v_mov_b32_e32 v179, v119
	v_and_b32_e32 v117, 0xffff0000, v113
	v_lshlrev_b32_e32 v112, 16, v110
	v_and_b32_e32 v113, 0xffff0000, v110
	v_and_b32_e32 v105, 0xffff0000, v105
	v_lshlrev_b32_e32 v170, 16, v102
	v_and_b32_e32 v171, 0xffff0000, v102
	v_pk_fma_f32 v[176:177], v[178:179], v[178:179], v[176:177]
	v_mov_b32_e32 v178, v104
	v_mov_b32_e32 v179, v116
	v_pk_mul_f32 v[172:173], v[112:113], v[112:113]
	v_pk_mul_f32 v[194:195], v[170:171], v[170:171]
	v_pk_fma_f32 v[176:177], v[178:179], v[178:179], v[176:177]
	v_mov_b32_e32 v178, v105
	v_mov_b32_e32 v179, v117
	v_lshlrev_b32_e32 v110, 16, v111
	v_and_b32_e32 v111, 0xffff0000, v111
	v_lshlrev_b32_e32 v102, 16, v103
	v_and_b32_e32 v103, 0xffff0000, v103
	v_pk_fma_f32 v[176:177], v[178:179], v[178:179], v[176:177]
	v_mov_b32_e32 v178, v194
	v_mov_b32_e32 v179, v172
	v_pk_mul_f32 v[174:175], v[110:111], v[110:111]
	v_pk_add_f32 v[176:177], v[178:179], v[176:177]
	v_pk_mul_f32 v[178:179], v[102:103], v[102:103]
	v_mov_b32_e32 v172, v195
	v_pk_add_f32 v[172:173], v[172:173], v[176:177]
	v_mov_b32_e32 v176, v178
	v_mov_b32_e32 v177, v174
	v_pk_add_f32 v[172:173], v[176:177], v[172:173]
	v_mov_b32_e32 v174, v179
	v_pk_add_f32 v[172:173], v[174:175], v[172:173]
	v_mov_b32_e32 v175, v173
	v_mov_b32_e32 v174, v172
	s_nop 1
	v_permlane32_swap_b32 v173, v175
	v_permlane32_swap_b32 v172, v174
	v_lshlrev_b32_e32 v196, 16, v92
	v_and_b32_e32 v197, 0xffff0000, v92
	v_lshlrev_b32_e32 v198, 16, v93
	v_and_b32_e32 v199, 0xffff0000, v93
	s_waitcnt lgkmcnt(0)
	v_pk_add_f32 v[172:173], v[172:173], v[174:175]
	v_mov_b32_e32 v175, v173
	v_mov_b32_e32 v174, v172
	s_nop 1
	v_permlane16_swap_b32 v173, v175
	v_permlane16_swap_b32 v172, v174
	v_lshlrev_b32_e32 v200, 16, v90
	v_and_b32_e32 v201, 0xffff0000, v90
	v_lshlrev_b32_e32 v202, 16, v91
	v_and_b32_e32 v203, 0xffff0000, v91
	s_waitcnt lgkmcnt(0)
	v_pk_add_f32 v[172:173], v[172:173], v[174:175]
	s_nop 1
	v_mov_b32_dpp v175, v173 row_ror:8 row_mask:0xf bank_mask:0xf
	v_mov_b32_dpp v174, v172 row_ror:8 row_mask:0xf bank_mask:0xf
	v_mov_b64_e32 v[90:91], s[50:51]
	v_lshlrev_b32_e32 v204, 16, v89
	v_and_b32_e32 v205, 0xffff0000, v89
	v_lshlrev_b32_e32 v122, 16, v114
	s_waitcnt lgkmcnt(0)
	v_pk_add_f32 v[172:173], v[172:173], v[174:175]
	s_nop 1
	v_mov_b32_dpp v175, v173 row_shl:4 row_mask:0xf bank_mask:0x5
	v_mov_b32_dpp v174, v172 row_shl:4 row_mask:0xf bank_mask:0x5
	v_mov_b32_dpp v175, v173 row_shr:4 row_mask:0xf bank_mask:0xa
	v_mov_b32_dpp v174, v172 row_shr:4 row_mask:0xf bank_mask:0xa
	v_and_b32_e32 v123, 0xffff0000, v114
	v_lshlrev_b32_e32 v120, 16, v115
	v_and_b32_e32 v121, 0xffff0000, v115
	v_lshlrev_b32_e32 v194, 16, v96
	s_waitcnt lgkmcnt(0)
	v_pk_add_f32 v[172:173], v[172:173], v[174:175]
	s_nop 1
	v_mov_b32_dpp v175, v173 quad_perm:[2,3,0,1] row_mask:0xf bank_mask:0xf
	v_mov_b32_dpp v174, v172 quad_perm:[2,3,0,1] row_mask:0xf bank_mask:0xf
	v_and_b32_e32 v195, 0xffff0000, v96
	v_lshlrev_b32_e32 v96, 16, v97
	v_and_b32_e32 v97, 0xffff0000, v97
	v_lshlrev_b32_e32 v114, 16, v100
	s_waitcnt lgkmcnt(0)
	v_pk_add_f32 v[92:93], v[172:173], v[174:175]
	s_nop 1
	v_mov_b32_dpp v173, v93 quad_perm:[1,0,3,2] row_mask:0xf bank_mask:0xf
	v_mov_b32_dpp v172, v92 quad_perm:[1,0,3,2] row_mask:0xf bank_mask:0xf
	v_lshlrev_b32_e32 v174, 16, v88
	v_and_b32_e32 v175, 0xffff0000, v88
	v_and_b32_e32 v115, 0xffff0000, v100
	v_lshlrev_b32_e32 v100, 16, v101
	s_waitcnt lgkmcnt(0)
	v_pk_add_f32 v[92:93], v[92:93], v[172:173]
	v_and_b32_e32 v101, 0xffff0000, v101
	v_pk_fma_f32 v[92:93], v[92:93], s[48:49], v[90:91] op_sel_hi:[1,0,0]
	v_lshlrev_b32_e32 v176, 16, v98
	v_mul_f32_e32 v88, 0x4b800000, v93
	v_cmp_gt_f32_e32 vcc, s5, v93
	v_cmp_gt_f32_e64 s[0:1], s5, v92
	v_and_b32_e32 v177, 0xffff0000, v98
	v_cndmask_b32_e32 v88, v93, v88, vcc
	v_mul_f32_e32 v93, 0x4b800000, v92
	v_rsq_f32_e32 v88, v88
	v_cndmask_b32_e64 v92, v92, v93, s[0:1]
	v_rsq_f32_e32 v92, v92
	v_lshlrev_b32_e32 v98, 16, v99
	v_mul_f32_e32 v89, 0x45800000, v88
	v_cndmask_b32_e32 v164, v88, v89, vcc
	v_mul_f32_e32 v88, 0x45800000, v92
	v_cndmask_b32_e64 v166, v92, v88, s[0:1]
	v_pk_mul_f32 v[88:89], v[164:165], v[132:133] op_sel_hi:[0,1]
	v_pk_mul_f32 v[92:93], v[164:165], v[134:135] op_sel_hi:[0,1]
	v_pk_mul_f32 v[88:89], v[28:29], v[88:89]
	v_pk_mul_f32 v[92:93], v[30:31], v[92:93]
	v_pk_fma_f32 v[88:89], v[40:41], v[88:89], v[122:123]
	v_pk_fma_f32 v[92:93], v[42:43], v[92:93], v[120:121]
	v_cvt_pk_bf16_f32 v88, v88, v89
	v_cvt_pk_bf16_f32 v89, v92, v93
	v_pk_mul_f32 v[92:93], v[166:167], v[140:141] op_sel_hi:[0,1]
	v_pk_mul_f32 v[108:109], v[166:167], v[108:109] op_sel_hi:[0,1]
	v_pk_mul_f32 v[92:93], v[28:29], v[92:93]
	v_pk_mul_f32 v[108:109], v[30:31], v[108:109]
	v_pk_fma_f32 v[92:93], v[40:41], v[92:93], v[194:195]
	v_pk_fma_f32 v[96:97], v[42:43], v[108:109], v[96:97]
	v_cvt_pk_bf16_f32 v92, v92, v93
	v_cvt_pk_bf16_f32 v93, v96, v97
	v_pk_mul_f32 v[96:97], v[164:165], v[136:137] op_sel_hi:[0,1]
	v_pk_mul_f32 v[108:109], v[164:165], v[138:139] op_sel_hi:[0,1]
	v_pk_mul_f32 v[96:97], v[20:21], v[96:97]
	v_pk_mul_f32 v[108:109], v[22:23], v[108:109]
	v_pk_fma_f32 v[96:97], v[52:53], v[96:97], v[114:115]
	v_pk_fma_f32 v[100:101], v[54:55], v[108:109], v[100:101]
	v_cvt_pk_bf16_f32 v96, v96, v97
	v_cvt_pk_bf16_f32 v97, v100, v101
	v_pk_mul_f32 v[100:101], v[166:167], v[142:143] op_sel_hi:[0,1]
	v_pk_mul_f32 v[106:107], v[166:167], v[106:107] op_sel_hi:[0,1]
	v_pk_mul_f32 v[100:101], v[20:21], v[100:101]
	v_pk_mul_f32 v[106:107], v[22:23], v[106:107]
	v_pk_fma_f32 v[100:101], v[52:53], v[100:101], v[196:197]
	v_pk_fma_f32 v[106:107], v[54:55], v[106:107], v[198:199]
	v_cvt_pk_bf16_f32 v100, v100, v101
	v_cvt_pk_bf16_f32 v101, v106, v107
	v_pk_mul_f32 v[106:107], v[164:165], v[118:119] op_sel_hi:[0,1]
	v_pk_mul_f32 v[108:109], v[164:165], v[116:117] op_sel_hi:[0,1]
	v_and_b32_e32 v99, 0xffff0000, v99
	v_pk_mul_f32 v[106:107], v[12:13], v[106:107]
	v_pk_mul_f32 v[108:109], v[14:15], v[108:109]
	v_pk_fma_f32 v[106:107], v[64:65], v[106:107], v[176:177]
	v_pk_fma_f32 v[98:99], v[66:67], v[108:109], v[98:99]
	v_cvt_pk_bf16_f32 v106, v106, v107
	v_cvt_pk_bf16_f32 v107, v98, v99
	v_pk_mul_f32 v[98:99], v[166:167], v[168:169] op_sel_hi:[0,1]
	v_pk_mul_f32 v[104:105], v[166:167], v[104:105] op_sel_hi:[0,1]
	v_pk_mul_f32 v[98:99], v[12:13], v[98:99]
	v_pk_mul_f32 v[104:105], v[14:15], v[104:105]
	v_pk_fma_f32 v[98:99], v[64:65], v[98:99], v[200:201]
	v_pk_fma_f32 v[104:105], v[66:67], v[104:105], v[202:203]
	v_cvt_pk_bf16_f32 v98, v98, v99
	v_cvt_pk_bf16_f32 v99, v104, v105
	v_pk_mul_f32 v[104:105], v[164:165], v[112:113] op_sel_hi:[0,1]
	v_pk_mul_f32 v[108:109], v[164:165], v[110:111] op_sel_hi:[0,1]
	v_lshlrev_b32_e32 v178, 16, v94
	v_and_b32_e32 v179, 0xffff0000, v94
	v_lshlrev_b32_e32 v94, 16, v95
	v_and_b32_e32 v95, 0xffff0000, v95
	v_pk_mul_f32 v[104:105], v[4:5], v[104:105]
	v_pk_mul_f32 v[108:109], v[6:7], v[108:109]
	v_pk_fma_f32 v[104:105], v[68:69], v[104:105], v[178:179]
	v_pk_fma_f32 v[94:95], v[70:71], v[108:109], v[94:95]
	v_cvt_pk_bf16_f32 v104, v104, v105
	v_cvt_pk_bf16_f32 v105, v94, v95
	v_pk_mul_f32 v[94:95], v[166:167], v[170:171] op_sel_hi:[0,1]
	v_pk_mul_f32 v[102:103], v[166:167], v[102:103] op_sel_hi:[0,1]
	v_pk_mul_f32 v[94:95], v[4:5], v[94:95]
	v_pk_mul_f32 v[102:103], v[6:7], v[102:103]
	v_and_b32_e32 v109, 0xffff0000, v88
	v_and_b32_e32 v115, 0xffff0000, v92
	v_pk_fma_f32 v[94:95], v[68:69], v[94:95], v[174:175]
	v_pk_fma_f32 v[102:103], v[70:71], v[102:103], v[204:205]
	v_lshlrev_b32_e32 v108, 16, v88
	v_lshlrev_b32_e32 v114, 16, v92
	v_mov_b32_e32 v118, v115
	v_mov_b32_e32 v119, v109
	v_cvt_pk_bf16_f32 v94, v94, v95
	v_cvt_pk_bf16_f32 v95, v102, v103
	v_lshlrev_b32_e32 v102, 16, v89
	v_lshlrev_b32_e32 v110, 16, v93
	v_mov_b32_e32 v116, v114
	v_mov_b32_e32 v117, v108
	v_pk_mul_f32 v[118:119], v[118:119], v[118:119]
	v_and_b32_e32 v103, 0xffff0000, v89
	v_and_b32_e32 v111, 0xffff0000, v93
	v_mov_b32_e32 v112, v110
	v_mov_b32_e32 v113, v102
	v_pk_fma_f32 v[116:117], v[116:117], v[116:117], v[118:119]
	v_lshlrev_b32_e32 v120, 16, v96
	v_lshlrev_b32_e32 v132, 16, v100
	v_mov_b32_e32 v196, v111
	v_mov_b32_e32 v197, v103
	v_pk_fma_f32 v[112:113], v[112:113], v[112:113], v[116:117]
	v_and_b32_e32 v121, 0xffff0000, v96
	v_and_b32_e32 v133, 0xffff0000, v100
	v_pk_fma_f32 v[112:113], v[196:197], v[196:197], v[112:113]
	v_mov_b32_e32 v198, v132
	v_mov_b32_e32 v199, v120
	v_lshlrev_b32_e32 v118, 16, v97
	v_lshlrev_b32_e32 v122, 16, v101
	v_mov_b32_e32 v200, v133
	v_mov_b32_e32 v201, v121
	v_pk_fma_f32 v[112:113], v[198:199], v[198:199], v[112:113]
	v_and_b32_e32 v119, 0xffff0000, v97
	v_and_b32_e32 v123, 0xffff0000, v101
	v_mov_b32_e32 v116, v122
	v_mov_b32_e32 v117, v118
	v_pk_fma_f32 v[112:113], v[200:201], v[200:201], v[112:113]
	v_lshlrev_b32_e32 v136, 16, v106
	v_lshlrev_b32_e32 v140, 16, v98
	v_mov_b32_e32 v196, v123
	v_mov_b32_e32 v197, v119
	v_pk_fma_f32 v[112:113], v[116:117], v[116:117], v[112:113]
	v_and_b32_e32 v137, 0xffff0000, v106
	v_and_b32_e32 v141, 0xffff0000, v98
	v_pk_fma_f32 v[112:113], v[196:197], v[196:197], v[112:113]
	v_mov_b32_e32 v198, v140
	v_mov_b32_e32 v199, v136
	v_lshlrev_b32_e32 v134, 16, v107
	v_lshlrev_b32_e32 v138, 16, v99
	v_mov_b32_e32 v200, v141
	v_mov_b32_e32 v201, v137
	v_pk_fma_f32 v[112:113], v[198:199], v[198:199], v[112:113]
	v_and_b32_e32 v135, 0xffff0000, v107
	v_and_b32_e32 v139, 0xffff0000, v99
	v_lshlrev_b32_e32 v170, 16, v104
	v_and_b32_e32 v171, 0xffff0000, v104
	v_lshlrev_b32_e32 v178, 16, v94
	v_and_b32_e32 v179, 0xffff0000, v94
	v_mov_b32_e32 v116, v138
	v_mov_b32_e32 v117, v134
	v_pk_fma_f32 v[112:113], v[200:201], v[200:201], v[112:113]
	v_pk_mul_f32 v[172:173], v[170:171], v[170:171]
	v_pk_mul_f32 v[194:195], v[178:179], v[178:179]
	v_mov_b32_e32 v196, v139
	v_mov_b32_e32 v197, v135
	v_pk_fma_f32 v[112:113], v[116:117], v[116:117], v[112:113]
	v_lshlrev_b32_e32 v142, 16, v105
	v_and_b32_e32 v143, 0xffff0000, v105
	v_lshlrev_b32_e32 v174, 16, v95
	v_and_b32_e32 v175, 0xffff0000, v95
	v_pk_fma_f32 v[112:113], v[196:197], v[196:197], v[112:113]
	v_mov_b32_e32 v116, v194
	v_mov_b32_e32 v117, v172
	v_pk_mul_f32 v[168:169], v[142:143], v[142:143]
	v_pk_mul_f32 v[176:177], v[174:175], v[174:175]
	v_pk_add_f32 v[112:113], v[116:117], v[112:113]
	v_mov_b32_e32 v172, v195
	v_pk_add_f32 v[112:113], v[172:173], v[112:113]
	v_mov_b32_e32 v116, v176
	v_mov_b32_e32 v117, v168
	v_pk_add_f32 v[112:113], v[116:117], v[112:113]
	v_mov_b32_e32 v168, v177
	v_pk_add_f32 v[112:113], v[168:169], v[112:113]
	v_mov_b32_e32 v117, v113
	v_mov_b32_e32 v116, v112
	s_nop 1
	v_permlane32_swap_b32 v113, v117
	v_permlane32_swap_b32 v112, v116
	v_lshl_add_u64 v[168:169], v[86:87], 0, s[14:15]
	v_lshl_add_u64 v[172:173], v[86:87], 0, s[16:17]
	v_lshl_add_u64 v[176:177], v[86:87], 0, s[18:19]
	v_lshl_add_u64 v[194:195], v[86:87], 0, s[20:21]
	s_waitcnt lgkmcnt(0)
	v_pk_add_f32 v[112:113], v[112:113], v[116:117]
	v_mov_b32_e32 v117, v113
	v_mov_b32_e32 v116, v112
	s_nop 1
	v_permlane16_swap_b32 v113, v117
	v_permlane16_swap_b32 v112, v116
	v_lshl_add_u64 v[196:197], v[86:87], 0, s[22:23]
	v_lshl_add_u64 v[198:199], v[86:87], 0, s[24:25]
	v_lshl_add_u64 v[200:201], v[86:87], 0, s[38:39]
	v_lshl_add_u64 v[202:203], v[86:87], 0, s[40:41]
	s_waitcnt lgkmcnt(0)
	v_pk_add_f32 v[112:113], v[112:113], v[116:117]
	s_nop 1
	v_mov_b32_dpp v117, v113 row_ror:8 row_mask:0xf bank_mask:0xf
	v_mov_b32_dpp v116, v112 row_ror:8 row_mask:0xf bank_mask:0xf
	v_add_co_u32_e32 v86, vcc, s6, v86
	v_add_u32_e32 v131, 2, v131
	s_nop 0
	v_addc_co_u32_e32 v87, vcc, 0, v87, vcc
	global_store_dwordx2 v[86:87], v[88:89], off
	s_waitcnt lgkmcnt(0)
	v_pk_add_f32 v[88:89], v[112:113], v[116:117]
	s_nop 1
	v_mov_b32_dpp v113, v89 row_shl:4 row_mask:0xf bank_mask:0x5
	v_mov_b32_dpp v112, v88 row_shl:4 row_mask:0xf bank_mask:0x5
	v_mov_b32_dpp v113, v89 row_shr:4 row_mask:0xf bank_mask:0xa
	v_mov_b32_dpp v112, v88 row_shr:4 row_mask:0xf bank_mask:0xa
	global_store_dwordx2 v[86:87], v[92:93], off offset:2048
	global_store_dwordx2 v[86:87], v[96:97], off offset:512
	global_store_dwordx2 v[86:87], v[100:101], off offset:2560
	global_store_dwordx2 v[86:87], v[106:107], off offset:1024
	global_store_dwordx2 v[86:87], v[98:99], off offset:3072
	global_store_dwordx2 v[86:87], v[104:105], off offset:1536
	global_store_dwordx2 v[86:87], v[94:95], off offset:3584
	v_pk_add_f32 v[86:87], v[32:33], 1.0 op_sel_hi:[1,0]
	v_pk_add_f32 v[94:95], v[34:35], 1.0 op_sel_hi:[1,0]
	s_waitcnt lgkmcnt(0)
	v_pk_add_f32 v[88:89], v[88:89], v[112:113]
	s_nop 1
	v_mov_b32_dpp v93, v89 quad_perm:[2,3,0,1] row_mask:0xf bank_mask:0xf
	v_mov_b32_dpp v92, v88 quad_perm:[2,3,0,1] row_mask:0xf bank_mask:0xf
	v_pk_add_f32 v[96:97], v[44:45], 1.0 op_sel_hi:[1,0]
	v_pk_add_f32 v[98:99], v[46:47], 1.0 op_sel_hi:[1,0]
	v_pk_add_f32 v[100:101], v[60:61], 1.0 op_sel_hi:[1,0]
	v_pk_add_f32 v[104:105], v[74:75], 1.0 op_sel_hi:[1,0]
	s_waitcnt lgkmcnt(0)
	v_pk_add_f32 v[88:89], v[88:89], v[92:93]
	s_nop 1
	v_mov_b32_dpp v93, v89 quad_perm:[1,0,3,2] row_mask:0xf bank_mask:0xf
	v_mov_b32_dpp v92, v88 quad_perm:[1,0,3,2] row_mask:0xf bank_mask:0xf
	v_lshl_add_u64 v[82:83], v[82:83], 0, s[10:11]
	v_lshl_add_u64 v[84:85], v[84:85], 0, s[10:11]
	s_waitcnt lgkmcnt(0)
	v_pk_add_f32 v[88:89], v[88:89], v[92:93]
	s_nop 0
	v_pk_fma_f32 v[88:89], v[88:89], s[48:49], v[90:91] op_sel_hi:[1,0,0]
	v_pk_add_f32 v[92:93], v[72:73], 1.0 op_sel_hi:[1,0]
	v_mul_f32_e32 v90, 0x4b800000, v89
	v_cmp_gt_f32_e32 vcc, s5, v89
	s_nop 1
	v_cndmask_b32_e32 v89, v89, v90, vcc
	v_rsq_f32_e32 v89, v89
	v_pk_add_f32 v[90:91], v[62:63], 1.0 op_sel_hi:[1,0]
	v_mul_f32_e32 v106, 0x45800000, v89
	v_cndmask_b32_e32 v106, v89, v106, vcc
	v_pk_mul_f32 v[108:109], v[106:107], v[108:109] op_sel_hi:[0,1]
	v_pk_mul_f32 v[102:103], v[106:107], v[102:103] op_sel_hi:[0,1]
	v_pk_mul_f32 v[108:109], v[24:25], v[108:109]
	v_pk_mul_f32 v[102:103], v[26:27], v[102:103]
	v_pk_fma_f32 v[108:109], v[86:87], v[108:109], v[36:37]
	v_pk_fma_f32 v[102:103], v[94:95], v[102:103], v[38:39]
	v_cvt_pk_bf16_f32 v108, v108, v109
	v_cvt_pk_bf16_f32 v109, v102, v103
	global_store_dwordx2 v[168:169], v[108:109], off
	v_pk_mul_f32 v[102:103], v[106:107], v[120:121] op_sel_hi:[0,1]
	v_pk_mul_f32 v[108:109], v[106:107], v[118:119] op_sel_hi:[0,1]
	v_pk_mul_f32 v[102:103], v[16:17], v[102:103]
	v_pk_mul_f32 v[108:109], v[18:19], v[108:109]
	v_pk_fma_f32 v[102:103], v[96:97], v[102:103], v[48:49]
	v_pk_fma_f32 v[108:109], v[98:99], v[108:109], v[50:51]
	v_cvt_pk_bf16_f32 v102, v102, v103
	v_cvt_pk_bf16_f32 v103, v108, v109
	global_store_dwordx2 v[172:173], v[102:103], off
	v_pk_mul_f32 v[102:103], v[106:107], v[136:137] op_sel_hi:[0,1]
	v_pk_mul_f32 v[108:109], v[106:107], v[134:135] op_sel_hi:[0,1]
	v_pk_mul_f32 v[102:103], v[8:9], v[102:103]
	v_pk_mul_f32 v[108:109], v[10:11], v[108:109]
	v_pk_fma_f32 v[102:103], v[100:101], v[102:103], v[56:57]
	v_pk_fma_f32 v[108:109], v[90:91], v[108:109], v[58:59]
	v_mul_f32_e32 v89, 0x4b800000, v88
	v_cmp_gt_f32_e32 vcc, s5, v88
	v_cvt_pk_bf16_f32 v102, v102, v103
	v_cvt_pk_bf16_f32 v103, v108, v109
	v_cndmask_b32_e32 v88, v88, v89, vcc
	global_store_dwordx2 v[176:177], v[102:103], off
	v_pk_mul_f32 v[102:103], v[106:107], v[170:171] op_sel_hi:[0,1]
	v_pk_mul_f32 v[106:107], v[106:107], v[142:143] op_sel_hi:[0,1]
	v_rsq_f32_e32 v108, v88
	v_pk_mul_f32 v[102:103], v[0:1], v[102:103]
	v_pk_mul_f32 v[106:107], v[2:3], v[106:107]
	v_pk_fma_f32 v[102:103], v[92:93], v[102:103], v[76:77]
	v_pk_fma_f32 v[106:107], v[104:105], v[106:107], v[78:79]
	v_cvt_pk_bf16_f32 v88, v102, v103
	v_cvt_pk_bf16_f32 v89, v106, v107
	global_store_dwordx2 v[194:195], v[88:89], off
	v_mul_f32_e32 v88, 0x45800000, v108
	v_cndmask_b32_e32 v88, v108, v88, vcc
	v_pk_mul_f32 v[102:103], v[88:89], v[114:115] op_sel_hi:[0,1]
	v_pk_mul_f32 v[102:103], v[24:25], v[102:103]
	v_cmp_ge_i32_e32 vcc, v131, v186
	v_pk_fma_f32 v[86:87], v[86:87], v[102:103], v[36:37]
	v_pk_mul_f32 v[102:103], v[88:89], v[110:111] op_sel_hi:[0,1]
	v_pk_mul_f32 v[102:103], v[26:27], v[102:103]
	v_cvt_pk_bf16_f32 v86, v86, v87
	v_pk_fma_f32 v[94:95], v[94:95], v[102:103], v[38:39]
	s_or_b64 s[12:13], vcc, s[12:13]
	v_cvt_pk_bf16_f32 v87, v94, v95
	global_store_dwordx2 v[196:197], v[86:87], off
	v_pk_mul_f32 v[86:87], v[88:89], v[132:133] op_sel_hi:[0,1]
	v_pk_mul_f32 v[94:95], v[88:89], v[122:123] op_sel_hi:[0,1]
	v_pk_mul_f32 v[86:87], v[16:17], v[86:87]
	v_pk_mul_f32 v[94:95], v[18:19], v[94:95]
	v_pk_fma_f32 v[86:87], v[96:97], v[86:87], v[48:49]
	v_pk_fma_f32 v[94:95], v[98:99], v[94:95], v[50:51]
	v_cvt_pk_bf16_f32 v86, v86, v87
	v_cvt_pk_bf16_f32 v87, v94, v95
	global_store_dwordx2 v[198:199], v[86:87], off
	v_pk_mul_f32 v[86:87], v[88:89], v[140:141] op_sel_hi:[0,1]
	v_pk_mul_f32 v[94:95], v[88:89], v[138:139] op_sel_hi:[0,1]
	v_pk_mul_f32 v[86:87], v[8:9], v[86:87]
	v_pk_mul_f32 v[94:95], v[10:11], v[94:95]
	v_pk_fma_f32 v[86:87], v[100:101], v[86:87], v[56:57]
	v_pk_fma_f32 v[90:91], v[90:91], v[94:95], v[58:59]
	v_cvt_pk_bf16_f32 v86, v86, v87
	v_cvt_pk_bf16_f32 v87, v90, v91
	global_store_dwordx2 v[200:201], v[86:87], off
	v_pk_mul_f32 v[86:87], v[88:89], v[178:179] op_sel_hi:[0,1]
	v_pk_mul_f32 v[88:89], v[88:89], v[174:175] op_sel_hi:[0,1]
	v_pk_mul_f32 v[86:87], v[0:1], v[86:87]
	v_pk_mul_f32 v[88:89], v[2:3], v[88:89]
	v_pk_fma_f32 v[86:87], v[92:93], v[86:87], v[76:77]
	v_pk_fma_f32 v[88:89], v[104:105], v[88:89], v[78:79]
	v_cvt_pk_bf16_f32 v86, v86, v87
	v_cvt_pk_bf16_f32 v87, v88, v89
	global_store_dwordx2 v[202:203], v[86:87], off
	s_andn2_b64 exec, exec, s[12:13]
	s_cbranch_execz .LBB0_1024
.LBB0_1022:
	v_lshl_add_u64 v[86:87], v[82:83], 0, v[80:81]
	v_add_u32_e32 v120, 0xffffe000, v131
	v_ashrrev_i32_e32 v120, 12, v120
	v_add_u32_e32 v120, 1, v120
	v_cmp_lt_i32_e32 vcc, s4, v131
	s_nop 1
	v_cndmask_b32_e32 v120, 0, v120, vcc
	v_cmp_ne_u32_e32 vcc, v120, v130
	s_and_saveexec_b64 s[0:1], vcc
	s_cbranch_execz .LBB0_1021
	v_mul_i32_i24_e32 v32, 0x2400, v120
	v_ashrrev_i32_e32 v33, 31, v32
	v_lshl_add_u64 v[32:33], v[32:33], 2, s[60:61]
	v_lshl_add_u64 v[60:61], v[32:33], 0, s[42:43]
	v_lshl_add_u64 v[72:73], v[32:33], 0, s[44:45]
	v_lshl_add_u64 v[74:75], v[32:33], 0, s[46:47]
	v_lshl_add_u64 v[32:33], v[60:61], 0, v[144:145]
	v_mov_b32_e32 v155, v145
	v_lshl_add_u64 v[34:35], v[72:73], 0, v[144:145]
	global_load_dwordx4 v[40:43], v[32:33], off
	global_load_dwordx4 v[36:39], v[34:35], off
	v_lshl_add_u64 v[32:33], v[74:75], 0, v[144:145]
	v_lshl_add_u64 v[44:45], v[60:61], 0, v[154:155]
	v_mov_b32_e32 v153, v145
	v_mov_b32_e32 v151, v145
	global_load_dwordx4 v[32:35], v[32:33], off
	s_nop 0
	global_load_dwordx4 v[52:55], v[44:45], off
	v_lshl_add_u64 v[44:45], v[72:73], 0, v[154:155]
	v_lshl_add_u64 v[46:47], v[74:75], 0, v[154:155]
	v_lshl_add_u64 v[56:57], v[60:61], 0, v[152:153]
	v_lshl_add_u64 v[58:59], v[72:73], 0, v[152:153]
	v_lshl_add_u64 v[62:63], v[74:75], 0, v[152:153]
	v_lshl_add_u64 v[68:69], v[60:61], 0, v[150:151]
	v_lshl_add_u64 v[72:73], v[72:73], 0, v[150:151]
	v_lshl_add_u64 v[74:75], v[74:75], 0, v[150:151]
	global_load_dwordx4 v[48:51], v[44:45], off
	s_nop 0
	global_load_dwordx4 v[44:47], v[46:47], off
	s_nop 0
	global_load_dwordx4 v[64:67], v[56:57], off
	s_nop 0
	global_load_dwordx4 v[56:59], v[58:59], off
	s_nop 0
	global_load_dwordx4 v[60:63], v[62:63], off
	s_nop 0
	global_load_dwordx4 v[68:71], v[68:69], off
	s_nop 0
	global_load_dwordx4 v[76:79], v[72:73], off
	s_nop 0
	global_load_dwordx4 v[72:75], v[74:75], off
	v_mov_b32_e32 v130, v120
	s_waitcnt vmcnt(0)
	s_branch .LBB0_1021
